# in/up GEMM: first-trip SP1 wait of a unit relaxed to vmcnt(32) (epilogue stores may drain under the first MFMA block)
# baseline (speedup 1.0000x reference)
.LBB0_205:
	s_ashr_i32 s55, s54, 31
	s_lshl_b64 s[56:57], s[54:55], 19
	s_add_u32 s56, s65, s56
	s_addc_u32 s57, s66, s57
	s_and_b64 s[58:59], s[38:39], exec
	s_cselect_b32 s9, s57, s23
	s_cselect_b32 s31, s56, s22
	s_ashr_i32 s53, s52, 31
	s_lshl_b64 s[58:59], s[52:53], 19
	s_add_u32 s58, s63, s58
	s_addc_u32 s59, s64, s59
	s_and_b64 s[60:61], s[38:39], exec
	s_cselect_b32 s41, s59, s43
	s_cselect_b32 s53, s58, s42
	s_add_u32 s22, s22, 0x40080
	s_addc_u32 s23, s23, 0
	s_add_u32 s55, s42, 0x100
	s_addc_u32 vcc_lo, s43, 0
	s_mov_b32 vcc_hi, -2
	v_lshl_add_u32 v152, s40, 8, v156
	v_ashrrev_i32_e32 v153, 31, v152
	v_lshl_add_u64 v[152:153], v[152:153], 2, s[44:45]
	global_load_dword v226, v[152:153], off
	global_load_dword v227, v[152:153], off offset:64
	global_load_dword v228, v[152:153], off offset:128
	global_load_dword v229, v[152:153], off offset:192
	global_load_dword v230, v[152:153], off offset:512
	global_load_dword v231, v[152:153], off offset:576
	global_load_dword v232, v[152:153], off offset:640
	global_load_dword v233, v[152:153], off offset:704
	s_add_u32 s10, s22, 0xfffc0080
	s_addc_u32 s11, s23, -1
	s_add_i32 s12, 0, 0x10000
	s_cmp_eq_u32 vcc_hi, 12
	s_cselect_b32 s61, s9, s11
	s_cselect_b32 s60, s31, s10
	v_add_u32_e32 v152, s12, v157
	s_cselect_b32 s43, s41, vcc_lo
	s_cselect_b32 s42, s53, s55
	s_add_i32 s13, 0, 0x14000
	ds_read_b128 v[140:143], v152
	ds_read_b128 v[144:147], v152 offset:1024
	ds_read_b128 v[148:151], v152 offset:2048
	ds_read_b128 v[160:163], v152 offset:3072
	v_add_u32_e32 v152, s13, v157
	ds_read_b128 v[164:167], v152
	ds_read_b128 v[168:171], v152 offset:1024
	ds_read_b128 v[172:175], v152 offset:2048
	ds_read_b128 v[176:179], v152 offset:3072
	s_add_u32 s10, s22, 0xfffc0000
	s_addc_u32 s11, s23, -1
	s_mov_b32 m0, s83
	s_nop 0
	global_load_lds_dwordx4 v136, s[10:11]
	s_mov_b32 m0, s95
	s_nop 0
	global_load_lds_dwordx4 v138, s[10:11]
	s_add_i32 m0, s75, 0xc000
	ds_read_b128 v[180:183], v159
	ds_read_b128 v[184:187], v159 offset:1024
	ds_read_b128 v[188:191], v159 offset:2048
	ds_read_b128 v[206:209], v159 offset:3072
	ds_read_b128 v[210:213], v159 offset:4096
	ds_read_b128 v[214:217], v159 offset:5120
	ds_read_b128 v[218:221], v159 offset:6144
	ds_read_b128 v[222:225], v159 offset:7168
	global_load_lds_dwordx4 v136, s[22:23]
	s_add_i32 m0, s75, 0xe000
	s_nop 0
	global_load_lds_dwordx4 v138, s[22:23]
	s_waitcnt vmcnt(32)
	s_waitcnt lgkmcnt(0)
	s_barrier
	s_setprio 1
	s_waitcnt lgkmcnt(0)
	v_mfma_f32_16x16x32_bf16 v[124:127], v[140:143], v[180:183], 0
	v_mfma_f32_16x16x32_bf16 v[120:123], v[148:151], v[180:183], 0
	v_mfma_f32_16x16x32_bf16 v[108:111], v[140:143], v[188:191], 0
	v_mfma_f32_16x16x32_bf16 v[104:107], v[148:151], v[188:191], 0
	v_mfma_f32_16x16x32_bf16 v[92:95], v[140:143], v[210:213], 0
	v_mfma_f32_16x16x32_bf16 v[88:91], v[148:151], v[210:213], 0
	v_mfma_f32_16x16x32_bf16 v[76:79], v[140:143], v[218:221], 0
	v_mfma_f32_16x16x32_bf16 v[72:75], v[148:151], v[218:221], 0
	v_mfma_f32_16x16x32_bf16 v[124:127], v[144:147], v[184:187], v[124:127]
	v_mfma_f32_16x16x32_bf16 v[120:123], v[160:163], v[184:187], v[120:123]
	v_mfma_f32_16x16x32_bf16 v[108:111], v[144:147], v[206:209], v[108:111]
	v_mfma_f32_16x16x32_bf16 v[104:107], v[160:163], v[206:209], v[104:107]
	v_mfma_f32_16x16x32_bf16 v[92:95], v[144:147], v[214:217], v[92:95]
	v_mfma_f32_16x16x32_bf16 v[88:91], v[160:163], v[214:217], v[88:91]
	v_mfma_f32_16x16x32_bf16 v[76:79], v[144:147], v[222:225], v[76:79]
	v_mfma_f32_16x16x32_bf16 v[72:75], v[160:163], v[222:225], v[72:75]
	s_setprio 0
	s_setprio 1
	v_mfma_f32_16x16x32_bf16 v[116:119], v[164:167], v[180:183], 0
	v_mfma_f32_16x16x32_bf16 v[112:115], v[172:175], v[180:183], 0
	v_mfma_f32_16x16x32_bf16 v[100:103], v[164:167], v[188:191], 0
	v_mfma_f32_16x16x32_bf16 v[96:99], v[172:175], v[188:191], 0
	v_mfma_f32_16x16x32_bf16 v[84:87], v[164:167], v[210:213], 0
	v_mfma_f32_16x16x32_bf16 v[80:83], v[172:175], v[210:213], 0
	v_mfma_f32_16x16x32_bf16 v[68:71], v[164:167], v[218:221], 0
	v_mfma_f32_16x16x32_bf16 v[64:67], v[172:175], v[218:221], 0
	v_mfma_f32_16x16x32_bf16 v[116:119], v[168:171], v[184:187], v[116:119]
	v_mfma_f32_16x16x32_bf16 v[112:115], v[176:179], v[184:187], v[112:115]
	v_mfma_f32_16x16x32_bf16 v[100:103], v[168:171], v[206:209], v[100:103]
	v_mfma_f32_16x16x32_bf16 v[96:99], v[176:179], v[206:209], v[96:99]
	v_mfma_f32_16x16x32_bf16 v[84:87], v[168:171], v[214:217], v[84:87]
	v_mfma_f32_16x16x32_bf16 v[80:83], v[176:179], v[214:217], v[80:83]
	v_mfma_f32_16x16x32_bf16 v[68:71], v[168:171], v[222:225], v[68:71]
	v_mfma_f32_16x16x32_bf16 v[64:67], v[176:179], v[222:225], v[64:67]
	s_setprio 0
	s_barrier
	s_add_i32 s10, s12, s67
	s_mov_b32 m0, s10
	ds_read_b128 v[180:183], v159 offset:16384
	ds_read_b128 v[184:187], v159 offset:17408
	ds_read_b128 v[188:191], v159 offset:18432
	ds_read_b128 v[206:209], v159 offset:19456
	ds_read_b128 v[210:213], v159 offset:20480
	ds_read_b128 v[214:217], v159 offset:21504
	ds_read_b128 v[218:221], v159 offset:22528
	ds_read_b128 v[222:225], v159 offset:23552
	global_load_lds_dwordx4 v192, s[42:43]
	s_add_i32 m0, s10, 0x2000
	s_add_u32 s10, s42, 0x40000
	s_addc_u32 s11, s43, 0
	s_add_i32 s12, s13, s67
	global_load_lds_dwordx4 v132, s[42:43]
	s_mov_b32 m0, s12
	s_nop 0
	global_load_lds_dwordx4 v192, s[10:11]
	s_add_i32 m0, s12, 0x2000
	s_nop 0
	global_load_lds_dwordx4 v132, s[10:11]
	s_waitcnt vmcnt(6)
	s_waitcnt lgkmcnt(0)
	s_barrier
	s_setprio 1
	s_waitcnt lgkmcnt(0)
	v_mfma_f32_16x16x32_bf16 v[60:63], v[140:143], v[180:183], 0
	v_mfma_f32_16x16x32_bf16 v[56:59], v[148:151], v[180:183], 0
	v_mfma_f32_16x16x32_bf16 v[44:47], v[140:143], v[188:191], 0
	v_mfma_f32_16x16x32_bf16 v[40:43], v[148:151], v[188:191], 0
	v_mfma_f32_16x16x32_bf16 v[28:31], v[140:143], v[210:213], 0
	v_mfma_f32_16x16x32_bf16 v[24:27], v[148:151], v[210:213], 0
	v_mfma_f32_16x16x32_bf16 v[12:15], v[140:143], v[218:221], 0
	v_mfma_f32_16x16x32_bf16 v[8:11], v[148:151], v[218:221], 0
	v_mfma_f32_16x16x32_bf16 v[60:63], v[144:147], v[184:187], v[60:63]
	v_mfma_f32_16x16x32_bf16 v[56:59], v[160:163], v[184:187], v[56:59]
	v_mfma_f32_16x16x32_bf16 v[44:47], v[144:147], v[206:209], v[44:47]
	v_mfma_f32_16x16x32_bf16 v[40:43], v[160:163], v[206:209], v[40:43]
	v_mfma_f32_16x16x32_bf16 v[28:31], v[144:147], v[214:217], v[28:31]
	v_mfma_f32_16x16x32_bf16 v[24:27], v[160:163], v[214:217], v[24:27]
	v_mfma_f32_16x16x32_bf16 v[12:15], v[144:147], v[222:225], v[12:15]
	v_mfma_f32_16x16x32_bf16 v[8:11], v[160:163], v[222:225], v[8:11]
	s_setprio 0
	s_setprio 1
	v_mfma_f32_16x16x32_bf16 v[52:55], v[164:167], v[180:183], 0
	v_mfma_f32_16x16x32_bf16 v[48:51], v[172:175], v[180:183], 0
	v_mfma_f32_16x16x32_bf16 v[36:39], v[164:167], v[188:191], 0
	v_mfma_f32_16x16x32_bf16 v[32:35], v[172:175], v[188:191], 0
	v_mfma_f32_16x16x32_bf16 v[20:23], v[164:167], v[210:213], 0
	v_mfma_f32_16x16x32_bf16 v[16:19], v[172:175], v[210:213], 0
	v_mfma_f32_16x16x32_bf16 v[4:7], v[164:167], v[218:221], 0
	v_mfma_f32_16x16x32_bf16 v[0:3], v[172:175], v[218:221], 0
	v_mfma_f32_16x16x32_bf16 v[52:55], v[168:171], v[184:187], v[52:55]
	v_mfma_f32_16x16x32_bf16 v[48:51], v[176:179], v[184:187], v[48:51]
	v_mfma_f32_16x16x32_bf16 v[36:39], v[168:171], v[206:209], v[36:39]
	v_mfma_f32_16x16x32_bf16 v[32:35], v[176:179], v[206:209], v[32:35]
	v_mfma_f32_16x16x32_bf16 v[20:23], v[168:171], v[214:217], v[20:23]
	v_mfma_f32_16x16x32_bf16 v[16:19], v[176:179], v[214:217], v[16:19]
	v_mfma_f32_16x16x32_bf16 v[4:7], v[168:171], v[222:225], v[4:7]
	v_mfma_f32_16x16x32_bf16 v[0:3], v[176:179], v[222:225], v[0:3]
	s_setprio 0
	s_barrier
	s_add_i32 s12, 0, 0x18000
	s_add_i32 s13, 0, 0x1c000
	v_add_u32_e32 v160, s12, v157
	v_add_u32_e32 v176, s13, v157
	ds_read_b128 v[140:143], v160
	ds_read_b128 v[144:147], v160 offset:1024
	ds_read_b128 v[148:151], v160 offset:2048
	ds_read_b128 v[160:163], v160 offset:3072
	ds_read_b128 v[164:167], v176
	ds_read_b128 v[168:171], v176 offset:1024
	ds_read_b128 v[172:175], v176 offset:2048
	ds_read_b128 v[176:179], v176 offset:3072
	s_mov_b32 m0, s75
	s_nop 0
	global_load_lds_dwordx4 v128, s[60:61]
	s_mov_b32 m0, s78
	s_nop 0
	global_load_lds_dwordx4 v130, s[60:61]
	s_add_u32 s10, s60, 0x40000
	s_addc_u32 s11, s61, 0
	s_mov_b32 m0, s79
	ds_read_b128 v[180:183], v159 offset:32768
	ds_read_b128 v[184:187], v159 offset:33792
	ds_read_b128 v[188:191], v159 offset:34816
	ds_read_b128 v[206:209], v159 offset:35840
	ds_read_b128 v[210:213], v159 offset:36864
	ds_read_b128 v[214:217], v159 offset:37888
	ds_read_b128 v[218:221], v159 offset:38912
	ds_read_b128 v[222:225], v159 offset:39936
	global_load_lds_dwordx4 v128, s[10:11]
	s_mov_b32 m0, s82
	s_nop 0
	global_load_lds_dwordx4 v130, s[10:11]
	s_waitcnt vmcnt(8)
	s_waitcnt lgkmcnt(0)
	s_barrier
	s_setprio 1
	s_waitcnt lgkmcnt(0)
	v_mfma_f32_16x16x32_bf16 v[124:127], v[140:143], v[180:183], v[124:127]
	v_mfma_f32_16x16x32_bf16 v[120:123], v[148:151], v[180:183], v[120:123]
	v_mfma_f32_16x16x32_bf16 v[108:111], v[140:143], v[188:191], v[108:111]
	v_mfma_f32_16x16x32_bf16 v[104:107], v[148:151], v[188:191], v[104:107]
	v_mfma_f32_16x16x32_bf16 v[92:95], v[140:143], v[210:213], v[92:95]
	v_mfma_f32_16x16x32_bf16 v[88:91], v[148:151], v[210:213], v[88:91]
	v_mfma_f32_16x16x32_bf16 v[76:79], v[140:143], v[218:221], v[76:79]
	v_mfma_f32_16x16x32_bf16 v[72:75], v[148:151], v[218:221], v[72:75]
	v_mfma_f32_16x16x32_bf16 v[124:127], v[144:147], v[184:187], v[124:127]
	v_mfma_f32_16x16x32_bf16 v[120:123], v[160:163], v[184:187], v[120:123]
	v_mfma_f32_16x16x32_bf16 v[108:111], v[144:147], v[206:209], v[108:111]
	v_mfma_f32_16x16x32_bf16 v[104:107], v[160:163], v[206:209], v[104:107]
	v_mfma_f32_16x16x32_bf16 v[92:95], v[144:147], v[214:217], v[92:95]
	v_mfma_f32_16x16x32_bf16 v[88:91], v[160:163], v[214:217], v[88:91]
	v_mfma_f32_16x16x32_bf16 v[76:79], v[144:147], v[222:225], v[76:79]
	v_mfma_f32_16x16x32_bf16 v[72:75], v[160:163], v[222:225], v[72:75]
	s_setprio 0
	s_setprio 1
	v_mfma_f32_16x16x32_bf16 v[116:119], v[164:167], v[180:183], v[116:119]
	v_mfma_f32_16x16x32_bf16 v[112:115], v[172:175], v[180:183], v[112:115]
	v_mfma_f32_16x16x32_bf16 v[100:103], v[164:167], v[188:191], v[100:103]
	v_mfma_f32_16x16x32_bf16 v[96:99], v[172:175], v[188:191], v[96:99]
	v_mfma_f32_16x16x32_bf16 v[84:87], v[164:167], v[210:213], v[84:87]
	v_mfma_f32_16x16x32_bf16 v[80:83], v[172:175], v[210:213], v[80:83]
	v_mfma_f32_16x16x32_bf16 v[68:71], v[164:167], v[218:221], v[68:71]
	v_mfma_f32_16x16x32_bf16 v[64:67], v[172:175], v[218:221], v[64:67]
	v_mfma_f32_16x16x32_bf16 v[116:119], v[168:171], v[184:187], v[116:119]
	v_mfma_f32_16x16x32_bf16 v[112:115], v[176:179], v[184:187], v[112:115]
	v_mfma_f32_16x16x32_bf16 v[100:103], v[168:171], v[206:209], v[100:103]
	v_mfma_f32_16x16x32_bf16 v[96:99], v[176:179], v[206:209], v[96:99]
	v_mfma_f32_16x16x32_bf16 v[84:87], v[168:171], v[214:217], v[84:87]
	v_mfma_f32_16x16x32_bf16 v[80:83], v[176:179], v[214:217], v[80:83]
	v_mfma_f32_16x16x32_bf16 v[68:71], v[168:171], v[222:225], v[68:71]
	v_mfma_f32_16x16x32_bf16 v[64:67], v[176:179], v[222:225], v[64:67]
	s_setprio 0
	s_barrier
	s_add_i32 s10, s12, s67
	s_add_i32 m0, s10, 0xffffff80
	ds_read_b128 v[180:183], v159 offset:49152
	ds_read_b128 v[184:187], v159 offset:50176
	ds_read_b128 v[188:191], v159 offset:51200
	ds_read_b128 v[206:209], v159 offset:52224
	ds_read_b128 v[210:213], v159 offset:53248
	ds_read_b128 v[214:217], v159 offset:54272
	ds_read_b128 v[218:221], v159 offset:55296
	ds_read_b128 v[222:225], v159 offset:56320
	global_load_lds_dwordx4 v192, s[42:43] offset:128
	s_add_i32 m0, s10, 0x1f80
	s_add_u32 s10, s42, 0x40080
	s_addc_u32 s11, s43, 0
	s_add_i32 s12, s13, s67
	global_load_lds_dwordx4 v132, s[42:43] offset:128
	s_mov_b32 m0, s12
	s_nop 0
	global_load_lds_dwordx4 v192, s[10:11]
	s_add_i32 m0, s12, 0x2000
	s_nop 0
	global_load_lds_dwordx4 v132, s[10:11]
	s_waitcnt vmcnt(6)
	s_waitcnt lgkmcnt(0)
	s_barrier
	s_setprio 1
	s_waitcnt lgkmcnt(0)
	v_mfma_f32_16x16x32_bf16 v[60:63], v[140:143], v[180:183], v[60:63]
	v_mfma_f32_16x16x32_bf16 v[56:59], v[148:151], v[180:183], v[56:59]
	v_mfma_f32_16x16x32_bf16 v[44:47], v[140:143], v[188:191], v[44:47]
	v_mfma_f32_16x16x32_bf16 v[40:43], v[148:151], v[188:191], v[40:43]
	v_mfma_f32_16x16x32_bf16 v[28:31], v[140:143], v[210:213], v[28:31]
	v_mfma_f32_16x16x32_bf16 v[24:27], v[148:151], v[210:213], v[24:27]
	v_mfma_f32_16x16x32_bf16 v[12:15], v[140:143], v[218:221], v[12:15]
	v_mfma_f32_16x16x32_bf16 v[8:11], v[148:151], v[218:221], v[8:11]
	v_mfma_f32_16x16x32_bf16 v[60:63], v[144:147], v[184:187], v[60:63]
	v_mfma_f32_16x16x32_bf16 v[56:59], v[160:163], v[184:187], v[56:59]
	v_mfma_f32_16x16x32_bf16 v[44:47], v[144:147], v[206:209], v[44:47]
	v_mfma_f32_16x16x32_bf16 v[40:43], v[160:163], v[206:209], v[40:43]
	v_mfma_f32_16x16x32_bf16 v[28:31], v[144:147], v[214:217], v[28:31]
	v_mfma_f32_16x16x32_bf16 v[24:27], v[160:163], v[214:217], v[24:27]
	v_mfma_f32_16x16x32_bf16 v[12:15], v[144:147], v[222:225], v[12:15]
	v_mfma_f32_16x16x32_bf16 v[8:11], v[160:163], v[222:225], v[8:11]
	s_setprio 0
	s_setprio 1
	v_mfma_f32_16x16x32_bf16 v[52:55], v[164:167], v[180:183], v[52:55]
	v_mfma_f32_16x16x32_bf16 v[48:51], v[172:175], v[180:183], v[48:51]
	v_mfma_f32_16x16x32_bf16 v[36:39], v[164:167], v[188:191], v[36:39]
	v_mfma_f32_16x16x32_bf16 v[32:35], v[172:175], v[188:191], v[32:35]
	v_mfma_f32_16x16x32_bf16 v[20:23], v[164:167], v[210:213], v[20:23]
	v_mfma_f32_16x16x32_bf16 v[16:19], v[172:175], v[210:213], v[16:19]
	v_mfma_f32_16x16x32_bf16 v[4:7], v[164:167], v[218:221], v[4:7]
	v_mfma_f32_16x16x32_bf16 v[0:3], v[172:175], v[218:221], v[0:3]
	v_mfma_f32_16x16x32_bf16 v[52:55], v[168:171], v[184:187], v[52:55]
	v_mfma_f32_16x16x32_bf16 v[48:51], v[176:179], v[184:187], v[48:51]
	v_mfma_f32_16x16x32_bf16 v[36:39], v[168:171], v[206:209], v[36:39]
	v_mfma_f32_16x16x32_bf16 v[32:35], v[176:179], v[206:209], v[32:35]
	v_mfma_f32_16x16x32_bf16 v[20:23], v[168:171], v[214:217], v[20:23]
	v_mfma_f32_16x16x32_bf16 v[16:19], v[176:179], v[214:217], v[16:19]
	v_mfma_f32_16x16x32_bf16 v[4:7], v[168:171], v[222:225], v[4:7]
	v_mfma_f32_16x16x32_bf16 v[0:3], v[176:179], v[222:225], v[0:3]
	s_setprio 0
	s_barrier
	s_add_i32 vcc_hi, vcc_hi, 2
	s_add_u32 s22, s22, 0x100
	s_addc_u32 s23, s23, 0
	s_add_u32 s55, s55, 0x100
	s_addc_u32 vcc_lo, vcc_lo, 0
	s_cmp_gt_u32 vcc_hi, 13

.LBB0_1143:
	s_ashr_i32 s49, s48, 31
	s_lshl_b64 s[6:7], s[48:49], 19
	s_add_u32 s50, s60, s6
	s_addc_u32 s51, s61, s7
	s_and_b64 s[6:7], s[38:39], exec
	s_cselect_b32 s5, s51, s31
	s_cselect_b32 s6, s50, s30
	s_ashr_i32 s47, s46, 31
	s_lshl_b64 s[8:9], s[46:47], 19
	s_add_u32 s52, s57, s8
	s_addc_u32 s53, s58, s9
	s_and_b64 s[8:9], s[38:39], exec
	s_cselect_b32 s7, s53, s41
	s_cselect_b32 s8, s52, s40
	s_add_u32 s30, s30, 0x40080
	s_addc_u32 s31, s31, 0
	s_add_u32 s9, s40, 0x100
	s_addc_u32 s23, s41, 0
	s_mov_b32 s47, -2
	v_lshl_add_u32 v226, s22, 8, v149
	v_ashrrev_i32_e32 v227, 31, v226
	v_lshl_add_u64 v[226:227], v[226:227], 2, s[34:35]
	global_load_dword v228, v[226:227], off
	global_load_dword v229, v[226:227], off offset:64
	global_load_dword v230, v[226:227], off offset:128
	global_load_dword v231, v[226:227], off offset:192
	global_load_dword v232, v[226:227], off offset:512
	global_load_dword v233, v[226:227], off offset:576
	global_load_dword v190, v[226:227], off offset:640
	global_load_dword v191, v[226:227], off offset:704
	s_add_u32 s10, s30, 0xfffc0080
	s_addc_u32 s11, s31, -1
	s_add_i32 s12, 0, 0x10000
	s_cmp_eq_u32 s47, 12
	s_cselect_b32 s55, s5, s11
	s_cselect_b32 s54, s6, s10
	v_add_u32_e32 v146, s12, v150
	s_cselect_b32 s41, s7, s23
	s_cselect_b32 s40, s8, s9
	s_add_i32 s13, 0, 0x14000
	ds_read_b128 v[138:141], v146
	ds_read_b128 v[142:145], v146 offset:1024
	ds_read_b128 v[154:157], v146 offset:2048
	ds_read_b128 v[158:161], v146 offset:3072
	v_add_u32_e32 v146, s13, v150
	ds_read_b128 v[162:165], v146
	ds_read_b128 v[166:169], v146 offset:1024
	ds_read_b128 v[170:173], v146 offset:2048
	ds_read_b128 v[174:177], v146 offset:3072
	s_add_u32 s10, s30, 0xfffc0000
	s_addc_u32 s11, s31, -1
	s_mov_b32 m0, s26
	s_nop 0
	global_load_lds_dwordx4 v134, s[10:11]
	s_mov_b32 m0, s67
	s_nop 0
	global_load_lds_dwordx4 v136, s[10:11]
	s_add_i32 m0, s63, 0xc000
	ds_read_b128 v[178:181], v152
	ds_read_b128 v[182:185], v152 offset:1024
	ds_read_b128 v[186:189], v152 offset:2048
	ds_read_b128 v[206:209], v152 offset:3072
	ds_read_b128 v[210:213], v152 offset:4096
	ds_read_b128 v[214:217], v152 offset:5120
	ds_read_b128 v[218:221], v152 offset:6144
	ds_read_b128 v[222:225], v152 offset:7168
	global_load_lds_dwordx4 v134, s[30:31]
	s_add_i32 m0, s63, 0xe000
	s_nop 0
	global_load_lds_dwordx4 v136, s[30:31]
	s_waitcnt vmcnt(32)
	s_waitcnt lgkmcnt(0)
	s_barrier
	s_setprio 1
	s_waitcnt lgkmcnt(0)
	v_mfma_f32_16x16x32_bf16 v[124:127], v[138:141], v[178:181], 0
	v_mfma_f32_16x16x32_bf16 v[120:123], v[154:157], v[178:181], 0
	v_mfma_f32_16x16x32_bf16 v[108:111], v[138:141], v[186:189], 0
	v_mfma_f32_16x16x32_bf16 v[104:107], v[154:157], v[186:189], 0
	v_mfma_f32_16x16x32_bf16 v[92:95], v[138:141], v[210:213], 0
	v_mfma_f32_16x16x32_bf16 v[88:91], v[154:157], v[210:213], 0
	v_mfma_f32_16x16x32_bf16 v[76:79], v[138:141], v[218:221], 0
	v_mfma_f32_16x16x32_bf16 v[72:75], v[154:157], v[218:221], 0
	v_mfma_f32_16x16x32_bf16 v[124:127], v[142:145], v[182:185], v[124:127]
	v_mfma_f32_16x16x32_bf16 v[120:123], v[158:161], v[182:185], v[120:123]
	v_mfma_f32_16x16x32_bf16 v[108:111], v[142:145], v[206:209], v[108:111]
	v_mfma_f32_16x16x32_bf16 v[104:107], v[158:161], v[206:209], v[104:107]
	v_mfma_f32_16x16x32_bf16 v[92:95], v[142:145], v[214:217], v[92:95]
	v_mfma_f32_16x16x32_bf16 v[88:91], v[158:161], v[214:217], v[88:91]
	v_mfma_f32_16x16x32_bf16 v[76:79], v[142:145], v[222:225], v[76:79]
	v_mfma_f32_16x16x32_bf16 v[72:75], v[158:161], v[222:225], v[72:75]
	s_setprio 0
	s_setprio 1
	v_mfma_f32_16x16x32_bf16 v[116:119], v[162:165], v[178:181], 0
	v_mfma_f32_16x16x32_bf16 v[112:115], v[170:173], v[178:181], 0
	v_mfma_f32_16x16x32_bf16 v[100:103], v[162:165], v[186:189], 0
	v_mfma_f32_16x16x32_bf16 v[96:99], v[170:173], v[186:189], 0
	v_mfma_f32_16x16x32_bf16 v[84:87], v[162:165], v[210:213], 0
	v_mfma_f32_16x16x32_bf16 v[80:83], v[170:173], v[210:213], 0
	v_mfma_f32_16x16x32_bf16 v[68:71], v[162:165], v[218:221], 0
	v_mfma_f32_16x16x32_bf16 v[64:67], v[170:173], v[218:221], 0
	v_mfma_f32_16x16x32_bf16 v[116:119], v[166:169], v[182:185], v[116:119]
	v_mfma_f32_16x16x32_bf16 v[112:115], v[174:177], v[182:185], v[112:115]
	v_mfma_f32_16x16x32_bf16 v[100:103], v[166:169], v[206:209], v[100:103]
	v_mfma_f32_16x16x32_bf16 v[96:99], v[174:177], v[206:209], v[96:99]
	v_mfma_f32_16x16x32_bf16 v[84:87], v[166:169], v[214:217], v[84:87]
	v_mfma_f32_16x16x32_bf16 v[80:83], v[174:177], v[214:217], v[80:83]
	v_mfma_f32_16x16x32_bf16 v[68:71], v[166:169], v[222:225], v[68:71]
	v_mfma_f32_16x16x32_bf16 v[64:67], v[174:177], v[222:225], v[64:67]
	s_setprio 0
	s_barrier
	s_add_i32 s10, s12, s62
	s_mov_b32 m0, s10
	ds_read_b128 v[178:181], v152 offset:16384
	ds_read_b128 v[182:185], v152 offset:17408
	ds_read_b128 v[186:189], v152 offset:18432
	ds_read_b128 v[206:209], v152 offset:19456
	ds_read_b128 v[210:213], v152 offset:20480
	ds_read_b128 v[214:217], v152 offset:21504
	ds_read_b128 v[218:221], v152 offset:22528
	ds_read_b128 v[222:225], v152 offset:23552
	global_load_lds_dwordx4 v192, s[40:41]
	s_add_i32 m0, s10, 0x2000
	s_add_u32 s10, s40, 0x40000
	s_addc_u32 s11, s41, 0
	s_add_i32 s12, s13, s62
	global_load_lds_dwordx4 v132, s[40:41]
	s_mov_b32 m0, s12
	s_nop 0
	global_load_lds_dwordx4 v192, s[10:11]
	s_add_i32 m0, s12, 0x2000
	s_nop 0
	global_load_lds_dwordx4 v132, s[10:11]
	s_waitcnt vmcnt(6)
	s_waitcnt lgkmcnt(0)
	s_barrier
	s_setprio 1
	s_waitcnt lgkmcnt(0)
	v_mfma_f32_16x16x32_bf16 v[60:63], v[138:141], v[178:181], 0
	v_mfma_f32_16x16x32_bf16 v[56:59], v[154:157], v[178:181], 0
	v_mfma_f32_16x16x32_bf16 v[44:47], v[138:141], v[186:189], 0
	v_mfma_f32_16x16x32_bf16 v[40:43], v[154:157], v[186:189], 0
	v_mfma_f32_16x16x32_bf16 v[28:31], v[138:141], v[210:213], 0
	v_mfma_f32_16x16x32_bf16 v[24:27], v[154:157], v[210:213], 0
	v_mfma_f32_16x16x32_bf16 v[12:15], v[138:141], v[218:221], 0
	v_mfma_f32_16x16x32_bf16 v[8:11], v[154:157], v[218:221], 0
	v_mfma_f32_16x16x32_bf16 v[60:63], v[142:145], v[182:185], v[60:63]
	v_mfma_f32_16x16x32_bf16 v[56:59], v[158:161], v[182:185], v[56:59]
	v_mfma_f32_16x16x32_bf16 v[44:47], v[142:145], v[206:209], v[44:47]
	v_mfma_f32_16x16x32_bf16 v[40:43], v[158:161], v[206:209], v[40:43]
	v_mfma_f32_16x16x32_bf16 v[28:31], v[142:145], v[214:217], v[28:31]
	v_mfma_f32_16x16x32_bf16 v[24:27], v[158:161], v[214:217], v[24:27]
	v_mfma_f32_16x16x32_bf16 v[12:15], v[142:145], v[222:225], v[12:15]
	v_mfma_f32_16x16x32_bf16 v[8:11], v[158:161], v[222:225], v[8:11]
	s_setprio 0
	s_setprio 1
	v_mfma_f32_16x16x32_bf16 v[52:55], v[162:165], v[178:181], 0
	v_mfma_f32_16x16x32_bf16 v[48:51], v[170:173], v[178:181], 0
	v_mfma_f32_16x16x32_bf16 v[36:39], v[162:165], v[186:189], 0
	v_mfma_f32_16x16x32_bf16 v[32:35], v[170:173], v[186:189], 0
	v_mfma_f32_16x16x32_bf16 v[20:23], v[162:165], v[210:213], 0
	v_mfma_f32_16x16x32_bf16 v[16:19], v[170:173], v[210:213], 0
	v_mfma_f32_16x16x32_bf16 v[4:7], v[162:165], v[218:221], 0
	v_mfma_f32_16x16x32_bf16 v[0:3], v[170:173], v[218:221], 0
	v_mfma_f32_16x16x32_bf16 v[52:55], v[166:169], v[182:185], v[52:55]
	v_mfma_f32_16x16x32_bf16 v[48:51], v[174:177], v[182:185], v[48:51]
	v_mfma_f32_16x16x32_bf16 v[36:39], v[166:169], v[206:209], v[36:39]
	v_mfma_f32_16x16x32_bf16 v[32:35], v[174:177], v[206:209], v[32:35]
	v_mfma_f32_16x16x32_bf16 v[20:23], v[166:169], v[214:217], v[20:23]
	v_mfma_f32_16x16x32_bf16 v[16:19], v[174:177], v[214:217], v[16:19]
	v_mfma_f32_16x16x32_bf16 v[4:7], v[166:169], v[222:225], v[4:7]
	v_mfma_f32_16x16x32_bf16 v[0:3], v[174:177], v[222:225], v[0:3]
	s_setprio 0
	s_barrier
	s_add_i32 s12, 0, 0x18000
	v_add_u32_e32 v146, s12, v150
	s_add_i32 s13, 0, 0x1c000
	ds_read_b128 v[138:141], v146
	ds_read_b128 v[142:145], v146 offset:1024
	ds_read_b128 v[154:157], v146 offset:2048
	ds_read_b128 v[158:161], v146 offset:3072
	v_add_u32_e32 v146, s13, v150
	ds_read_b128 v[162:165], v146
	ds_read_b128 v[166:169], v146 offset:1024
	ds_read_b128 v[170:173], v146 offset:2048
	ds_read_b128 v[174:177], v146 offset:3072
	s_mov_b32 m0, s63
	s_nop 0
	global_load_lds_dwordx4 v128, s[54:55]
	s_mov_b32 m0, s64
	s_nop 0
	global_load_lds_dwordx4 v130, s[54:55]
	s_add_u32 s10, s54, 0x40000
	s_addc_u32 s11, s55, 0
	s_mov_b32 m0, s65
	ds_read_b128 v[178:181], v152 offset:32768
	ds_read_b128 v[182:185], v152 offset:33792
	ds_read_b128 v[186:189], v152 offset:34816
	ds_read_b128 v[206:209], v152 offset:35840
	ds_read_b128 v[210:213], v152 offset:36864
	ds_read_b128 v[214:217], v152 offset:37888
	ds_read_b128 v[218:221], v152 offset:38912
	ds_read_b128 v[222:225], v152 offset:39936
	global_load_lds_dwordx4 v128, s[10:11]
	s_mov_b32 m0, s66
	s_nop 0
	global_load_lds_dwordx4 v130, s[10:11]
	s_waitcnt vmcnt(8)
	s_waitcnt lgkmcnt(0)
	s_barrier
	s_setprio 1
	s_waitcnt lgkmcnt(0)
	v_mfma_f32_16x16x32_bf16 v[124:127], v[138:141], v[178:181], v[124:127]
	v_mfma_f32_16x16x32_bf16 v[120:123], v[154:157], v[178:181], v[120:123]
	v_mfma_f32_16x16x32_bf16 v[108:111], v[138:141], v[186:189], v[108:111]
	v_mfma_f32_16x16x32_bf16 v[104:107], v[154:157], v[186:189], v[104:107]
	v_mfma_f32_16x16x32_bf16 v[92:95], v[138:141], v[210:213], v[92:95]
	v_mfma_f32_16x16x32_bf16 v[88:91], v[154:157], v[210:213], v[88:91]
	v_mfma_f32_16x16x32_bf16 v[76:79], v[138:141], v[218:221], v[76:79]
	v_mfma_f32_16x16x32_bf16 v[72:75], v[154:157], v[218:221], v[72:75]
	v_mfma_f32_16x16x32_bf16 v[124:127], v[142:145], v[182:185], v[124:127]
	v_mfma_f32_16x16x32_bf16 v[120:123], v[158:161], v[182:185], v[120:123]
	v_mfma_f32_16x16x32_bf16 v[108:111], v[142:145], v[206:209], v[108:111]
	v_mfma_f32_16x16x32_bf16 v[104:107], v[158:161], v[206:209], v[104:107]
	v_mfma_f32_16x16x32_bf16 v[92:95], v[142:145], v[214:217], v[92:95]
	v_mfma_f32_16x16x32_bf16 v[88:91], v[158:161], v[214:217], v[88:91]
	v_mfma_f32_16x16x32_bf16 v[76:79], v[142:145], v[222:225], v[76:79]
	v_mfma_f32_16x16x32_bf16 v[72:75], v[158:161], v[222:225], v[72:75]
	s_setprio 0
	s_setprio 1
	v_mfma_f32_16x16x32_bf16 v[116:119], v[162:165], v[178:181], v[116:119]
	v_mfma_f32_16x16x32_bf16 v[112:115], v[170:173], v[178:181], v[112:115]
	v_mfma_f32_16x16x32_bf16 v[100:103], v[162:165], v[186:189], v[100:103]
	v_mfma_f32_16x16x32_bf16 v[96:99], v[170:173], v[186:189], v[96:99]
	v_mfma_f32_16x16x32_bf16 v[84:87], v[162:165], v[210:213], v[84:87]
	v_mfma_f32_16x16x32_bf16 v[80:83], v[170:173], v[210:213], v[80:83]
	v_mfma_f32_16x16x32_bf16 v[68:71], v[162:165], v[218:221], v[68:71]
	v_mfma_f32_16x16x32_bf16 v[64:67], v[170:173], v[218:221], v[64:67]
	v_mfma_f32_16x16x32_bf16 v[116:119], v[166:169], v[182:185], v[116:119]
	v_mfma_f32_16x16x32_bf16 v[112:115], v[174:177], v[182:185], v[112:115]
	v_mfma_f32_16x16x32_bf16 v[100:103], v[166:169], v[206:209], v[100:103]
	v_mfma_f32_16x16x32_bf16 v[96:99], v[174:177], v[206:209], v[96:99]
	v_mfma_f32_16x16x32_bf16 v[84:87], v[166:169], v[214:217], v[84:87]
	v_mfma_f32_16x16x32_bf16 v[80:83], v[174:177], v[214:217], v[80:83]
	v_mfma_f32_16x16x32_bf16 v[68:71], v[166:169], v[222:225], v[68:71]
	v_mfma_f32_16x16x32_bf16 v[64:67], v[174:177], v[222:225], v[64:67]
	s_setprio 0
	s_barrier
	s_add_i32 s10, s12, s62
	s_add_i32 m0, s10, 0xffffff80
	ds_read_b128 v[178:181], v152 offset:49152
	ds_read_b128 v[182:185], v152 offset:50176
	ds_read_b128 v[186:189], v152 offset:51200
	ds_read_b128 v[206:209], v152 offset:52224
	ds_read_b128 v[210:213], v152 offset:53248
	ds_read_b128 v[214:217], v152 offset:54272
	ds_read_b128 v[218:221], v152 offset:55296
	ds_read_b128 v[222:225], v152 offset:56320
	global_load_lds_dwordx4 v192, s[40:41] offset:128
	s_add_i32 m0, s10, 0x1f80
	s_add_u32 s10, s40, 0x40080
	s_addc_u32 s11, s41, 0
	s_add_i32 s12, s13, s62
	global_load_lds_dwordx4 v132, s[40:41] offset:128
	s_mov_b32 m0, s12
	s_nop 0
	global_load_lds_dwordx4 v192, s[10:11]
	s_add_i32 m0, s12, 0x2000
	s_nop 0
	global_load_lds_dwordx4 v132, s[10:11]
	s_waitcnt vmcnt(6)
	s_waitcnt lgkmcnt(0)
	s_barrier
	s_setprio 1
	s_waitcnt lgkmcnt(0)
	v_mfma_f32_16x16x32_bf16 v[60:63], v[138:141], v[178:181], v[60:63]
	v_mfma_f32_16x16x32_bf16 v[56:59], v[154:157], v[178:181], v[56:59]
	v_mfma_f32_16x16x32_bf16 v[44:47], v[138:141], v[186:189], v[44:47]
	v_mfma_f32_16x16x32_bf16 v[40:43], v[154:157], v[186:189], v[40:43]
	v_mfma_f32_16x16x32_bf16 v[28:31], v[138:141], v[210:213], v[28:31]
	v_mfma_f32_16x16x32_bf16 v[24:27], v[154:157], v[210:213], v[24:27]
	v_mfma_f32_16x16x32_bf16 v[12:15], v[138:141], v[218:221], v[12:15]
	v_mfma_f32_16x16x32_bf16 v[8:11], v[154:157], v[218:221], v[8:11]
	v_mfma_f32_16x16x32_bf16 v[60:63], v[142:145], v[182:185], v[60:63]
	v_mfma_f32_16x16x32_bf16 v[56:59], v[158:161], v[182:185], v[56:59]
	v_mfma_f32_16x16x32_bf16 v[44:47], v[142:145], v[206:209], v[44:47]
	v_mfma_f32_16x16x32_bf16 v[40:43], v[158:161], v[206:209], v[40:43]
	v_mfma_f32_16x16x32_bf16 v[28:31], v[142:145], v[214:217], v[28:31]
	v_mfma_f32_16x16x32_bf16 v[24:27], v[158:161], v[214:217], v[24:27]
	v_mfma_f32_16x16x32_bf16 v[12:15], v[142:145], v[222:225], v[12:15]
	v_mfma_f32_16x16x32_bf16 v[8:11], v[158:161], v[222:225], v[8:11]
	s_setprio 0
	s_setprio 1
	v_mfma_f32_16x16x32_bf16 v[52:55], v[162:165], v[178:181], v[52:55]
	v_mfma_f32_16x16x32_bf16 v[48:51], v[170:173], v[178:181], v[48:51]
	v_mfma_f32_16x16x32_bf16 v[36:39], v[162:165], v[186:189], v[36:39]
	v_mfma_f32_16x16x32_bf16 v[32:35], v[170:173], v[186:189], v[32:35]
	v_mfma_f32_16x16x32_bf16 v[20:23], v[162:165], v[210:213], v[20:23]
	v_mfma_f32_16x16x32_bf16 v[16:19], v[170:173], v[210:213], v[16:19]
	v_mfma_f32_16x16x32_bf16 v[4:7], v[162:165], v[218:221], v[4:7]
	v_mfma_f32_16x16x32_bf16 v[0:3], v[170:173], v[218:221], v[0:3]
	v_mfma_f32_16x16x32_bf16 v[52:55], v[166:169], v[182:185], v[52:55]
	v_mfma_f32_16x16x32_bf16 v[48:51], v[174:177], v[182:185], v[48:51]
	v_mfma_f32_16x16x32_bf16 v[36:39], v[166:169], v[206:209], v[36:39]
	v_mfma_f32_16x16x32_bf16 v[32:35], v[174:177], v[206:209], v[32:35]
	v_mfma_f32_16x16x32_bf16 v[20:23], v[166:169], v[214:217], v[20:23]
	v_mfma_f32_16x16x32_bf16 v[16:19], v[174:177], v[214:217], v[16:19]
	v_mfma_f32_16x16x32_bf16 v[4:7], v[166:169], v[222:225], v[4:7]
	v_mfma_f32_16x16x32_bf16 v[0:3], v[174:177], v[222:225], v[0:3]
	s_setprio 0
	s_barrier
	s_add_i32 s47, s47, 2
	s_add_u32 s30, s30, 0x100
	s_addc_u32 s31, s31, 0
	s_add_u32 s9, s9, 0x100
	s_addc_u32 s23, s23, 0
	s_cmp_gt_u32 s47, 13
